# seam 8 also per-XCD; the P8-read vs P10-write order is kept by a chip-wide arrival word checked at seam 9
# speedup vs baseline: 1.0034x; 1.0034x over previous
; __device__ __forceinline__ unsigned xb_ld(unsigned* p)              { return __hip_atomic_load(p, __ATOMIC_RELAXED, __HIP_MEMORY_SCOPE_AGENT); }
; __device__ __forceinline__ unsigned xb_add(unsigned* p, unsigned v) { return __hip_atomic_fetch_add(p, v, __ATOMIC_RELAXED, __HIP_MEMORY_SCOPE_AGENT); }
; #define XB_SPIN(cond, bar) do { unsigned _sp = 0; while (cond) { __builtin_amdgcn_s_sleep(1); \
;     if ((++_sp & 255u) == 0u) { if (xb_ld(&(bar)[XB_TMO])) break; if (_sp > XB_SPIN_CAP) { atomicAdd(&(bar)[XB_TMO], 1u); break; } } } } while (0)
; #define SEAM(k) do { if (IN(k) && IN((k) + 1)) xcd_barrier(bar); } while (0)
; __device__ __forceinline__ void xcd_barrier(const XcdBarrier& b) {
;     asm volatile("s_waitcnt vmcnt(0)" ::: "memory");
;     __syncthreads();
;     if (threadIdx.x == 0) {
;         unsigned* bar = b.bar;
;         __builtin_amdgcn_s_waitcnt(0);
;         unsigned nloc = b.st[0], nx = b.st[1];
;         if (nloc == 0u) { xcd_barrier_complete(bar, b.x, nloc, nx); b.st[0] = nloc; b.st[1] = nx; }
;         const unsigned old = xb_add(&bar[XB_XSUB(b.x)], 1u);
;         const unsigned gen = old / nloc;
;         if (old + 1u == (gen + 1u) * nloc) {
;             __builtin_amdgcn_fence(__ATOMIC_RELEASE, "agent");
;             asm volatile("s_waitcnt vmcnt(0)" ::: "memory");
;             const unsigned og = xb_add(&bar[XB_TOP], 1u);
;             const unsigned tg = og / nx;
;             if (og + 1u == (tg + 1u) * nx) xb_add(&bar[XB_TOPGEN], 1u);
;             else XB_SPIN(xb_ld(&bar[XB_TOPGEN]) == tg, bar);
;             __builtin_amdgcn_fence(__ATOMIC_ACQUIRE, "agent");
;             xb_add(&bar[XB_XGEN(b.x)], 1u);
;             asm volatile("s_waitcnt vmcnt(0)" ::: "memory");
;         } else {
;             XB_SPIN(xb_ld(&bar[XB_XGEN(b.x)]) == gen, bar);
;             __builtin_amdgcn_fence(__ATOMIC_ACQUIRE, "agent");
;             asm volatile("s_waitcnt vmcnt(0)" ::: "memory");
;         }
;     }
;     __syncthreads();
; }
; __global__ void __launch_bounds__(NWAVES * 64, 2) mega_fwd(Args args) {
;     ...
;     SEAM(8);
;     if (IN(9)) { pg8::Gemm g{MG, Wout, M, DM, DM, DM, DM, 0, 0, 1}; pg8::StaticOrder S; S.init(M, DM, 1, G, bx);
;         pg8::EpiResid<true> E{nullptr, XB, ss2, 1.0f}; pg8::gemm_phase<pg8::EpiResid<true>, true>(lds, g, S, E); }
.LBB0_1138:
	s_cmp_gt_i32 s85, 9
	s_cselect_b64 s[0:1], -1, 0
	s_and_b64 s[2:3], s[4:5], s[0:1]
	s_andn2_b64 vcc, exec, s[2:3]
	s_cbranch_vccnz .LBB0_1192
	s_waitcnt vmcnt(0)
	s_waitcnt vmcnt(0) lgkmcnt(0)
	s_barrier
	s_and_saveexec_b64 s[2:3], s[74:75]
	s_cbranch_execz .LBB0_1191
	s_getreg_b32 s4, hwreg(HW_REG_XCC_ID, 0, 4)
	s_and_b32 s4, s4, 7
	s_lshl_b32 s4, s4, 8
	s_add_u32 s6, s66, 0xfd09000
	s_addc_u32 s7, s67, 0
	v_mov_b32_e32 v1, s4
	v_mov_b32_e32 v2, 1
	v_mov_b32_e32 v4, 0x20160
	ds_read_b32 v4, v4
	global_atomic_add v1, v2, s[6:7]
	v_mov_b32_e32 v5, 0x1000
	global_atomic_add v5, v2, s[6:7]
	s_waitcnt lgkmcnt(0)
	v_readfirstlane_b32 s5, v4
	s_mov_b32 s8, 0
	s_nop 2
	s_mul_i32 s5, s5, 1

; __device__ __forceinline__ unsigned xb_ld(unsigned* p)              { return __hip_atomic_load(p, __ATOMIC_RELAXED, __HIP_MEMORY_SCOPE_AGENT); }
; __device__ __forceinline__ unsigned xb_add(unsigned* p, unsigned v) { return __hip_atomic_fetch_add(p, v, __ATOMIC_RELAXED, __HIP_MEMORY_SCOPE_AGENT); }
; #define XB_SPIN(cond, bar) do { unsigned _sp = 0; while (cond) { __builtin_amdgcn_s_sleep(1); \
;     if ((++_sp & 255u) == 0u) { if (xb_ld(&(bar)[XB_TMO])) break; if (_sp > XB_SPIN_CAP) { atomicAdd(&(bar)[XB_TMO], 1u); break; } } } } while (0)
; __device__ __forceinline__ void xcd_barrier(const XcdBarrier& b) {
;     asm volatile("s_waitcnt vmcnt(0)" ::: "memory");
;     __syncthreads();
;     if (threadIdx.x == 0) {
;         unsigned* bar = b.bar;
;         __builtin_amdgcn_s_waitcnt(0);
;         unsigned nloc = b.st[0], nx = b.st[1];
;         if (nloc == 0u) { xcd_barrier_complete(bar, b.x, nloc, nx); b.st[0] = nloc; b.st[1] = nx; }
;         const unsigned old = xb_add(&bar[XB_XSUB(b.x)], 1u);
;         const unsigned gen = old / nloc;
;         if (old + 1u == (gen + 1u) * nloc) {
;             __builtin_amdgcn_fence(__ATOMIC_RELEASE, "agent");
;             asm volatile("s_waitcnt vmcnt(0)" ::: "memory");
;             const unsigned og = xb_add(&bar[XB_TOP], 1u);
;             const unsigned tg = og / nx;
;             if (og + 1u == (tg + 1u) * nx) xb_add(&bar[XB_TOPGEN], 1u);
;             else XB_SPIN(xb_ld(&bar[XB_TOPGEN]) == tg, bar);
;             __builtin_amdgcn_fence(__ATOMIC_ACQUIRE, "agent");
;             xb_add(&bar[XB_XGEN(b.x)], 1u);
;             asm volatile("s_waitcnt vmcnt(0)" ::: "memory");
;         } else {
;             XB_SPIN(xb_ld(&bar[XB_XGEN(b.x)]) == gen, bar);
;             __builtin_amdgcn_fence(__ATOMIC_ACQUIRE, "agent");
;             asm volatile("s_waitcnt vmcnt(0)" ::: "memory");
;         }
;     }
;     __syncthreads();
; }
.Lls8_ok:
	buffer_inv sc1
	s_waitcnt vmcnt(0)
.LBB0_1191:
	s_or_b64 exec, exec, s[2:3]
	s_waitcnt lgkmcnt(0)
	s_barrier

; __device__ __forceinline__ unsigned xb_ld(unsigned* p)              { return __hip_atomic_load(p, __ATOMIC_RELAXED, __HIP_MEMORY_SCOPE_AGENT); }
; __device__ __forceinline__ unsigned xb_add(unsigned* p, unsigned v) { return __hip_atomic_fetch_add(p, v, __ATOMIC_RELAXED, __HIP_MEMORY_SCOPE_AGENT); }
; #define XB_SPIN(cond, bar) do { unsigned _sp = 0; while (cond) { __builtin_amdgcn_s_sleep(1); \
;     if ((++_sp & 255u) == 0u) { if (xb_ld(&(bar)[XB_TMO])) break; if (_sp > XB_SPIN_CAP) { atomicAdd(&(bar)[XB_TMO], 1u); break; } } } } while (0)
; #define SEAM(k) do { if (IN(k) && IN((k) + 1)) xcd_barrier(bar); } while (0)
; __device__ __forceinline__ void xcd_barrier(const XcdBarrier& b) {
;     asm volatile("s_waitcnt vmcnt(0)" ::: "memory");
;     __syncthreads();
;     if (threadIdx.x == 0) {
;         unsigned* bar = b.bar;
;         __builtin_amdgcn_s_waitcnt(0);
;         unsigned nloc = b.st[0], nx = b.st[1];
;         if (nloc == 0u) { xcd_barrier_complete(bar, b.x, nloc, nx); b.st[0] = nloc; b.st[1] = nx; }
;         const unsigned old = xb_add(&bar[XB_XSUB(b.x)], 1u);
;         const unsigned gen = old / nloc;
;         if (old + 1u == (gen + 1u) * nloc) {
;             __builtin_amdgcn_fence(__ATOMIC_RELEASE, "agent");
;             asm volatile("s_waitcnt vmcnt(0)" ::: "memory");
;             const unsigned og = xb_add(&bar[XB_TOP], 1u);
;             const unsigned tg = og / nx;
;             if (og + 1u == (tg + 1u) * nx) xb_add(&bar[XB_TOPGEN], 1u);
;             else XB_SPIN(xb_ld(&bar[XB_TOPGEN]) == tg, bar);
;             __builtin_amdgcn_fence(__ATOMIC_ACQUIRE, "agent");
;             xb_add(&bar[XB_XGEN(b.x)], 1u);
;             asm volatile("s_waitcnt vmcnt(0)" ::: "memory");
;         } else {
;             XB_SPIN(xb_ld(&bar[XB_XGEN(b.x)]) == gen, bar);
;             __builtin_amdgcn_fence(__ATOMIC_ACQUIRE, "agent");
;             asm volatile("s_waitcnt vmcnt(0)" ::: "memory");
;         }
;     }
;     __syncthreads();
; }
; __global__ void __launch_bounds__(NWAVES * 64, 2) mega_fwd(Args args) {
;     ...
;     SEAM(9);
;     if (IN(10)) { pg8::Gemm g{XB, W2gu, M, 2 * FF, DM, DM, DM, 0, 0, 1}; pg8::StaticOrder S; S.init(M, 2 * FF, 1, G, bx);
;         pg8::EpiSwiglu E{ss2, ACT}; pg8::gemm_phase<pg8::EpiSwiglu, true>(lds, g, S, E);
.LBB0_1235:
	s_cmp_gt_i32 s85, 10
	s_cselect_b64 s[2:3], -1, 0
	s_and_b64 s[0:1], s[0:1], s[2:3]
	s_andn2_b64 vcc, exec, s[0:1]
	s_cbranch_vccnz .LBB0_1289
	s_waitcnt vmcnt(0)
	s_waitcnt vmcnt(0) lgkmcnt(0)
	s_barrier
	s_and_saveexec_b64 s[0:1], s[74:75]
	s_cbranch_execz .LBB0_1288
	s_getreg_b32 s4, hwreg(HW_REG_XCC_ID, 0, 4)
	s_and_b32 s4, s4, 7
	s_lshl_b32 s4, s4, 8
	s_add_u32 s6, s66, 0xfd09000
	s_addc_u32 s7, s67, 0
	v_mov_b32_e32 v1, s4
	v_mov_b32_e32 v2, 1
	v_mov_b32_e32 v4, 0x20160
	ds_read_b32 v4, v4
	global_atomic_add v1, v2, s[6:7]
	s_waitcnt lgkmcnt(0)
	v_readfirstlane_b32 s5, v4
	s_mov_b32 s8, 0
	s_nop 2
	s_mul_i32 s5, s5, 2
.Lls9_spin:
	global_load_dword v3, v1, s[6:7] sc1
	v_mov_b32_e32 v5, 0x1000
	global_load_dword v6, v5, s[6:7] sc1
	s_waitcnt vmcnt(0)
	v_readfirstlane_b32 s9, v3
	v_readfirstlane_b32 s4, v6
	s_nop 3
	s_cmp_ge_u32 s9, s5
	s_cselect_b32 s9, 1, 0
	s_cmp_ge_u32 s4, s86
	s_cselect_b32 s4, 1, 0
	s_and_b32 s9, s9, s4
	s_cmp_lg_u32 s9, 0
	s_cbranch_scc1 .Lls9_ok
	s_sleep 1
	s_add_i32 s8, s8, 1
	s_cmp_lt_u32 s8, 0x20000
	s_cbranch_scc1 .Lls9_spin

; __device__ __forceinline__ unsigned xb_ld(unsigned* p)              { return __hip_atomic_load(p, __ATOMIC_RELAXED, __HIP_MEMORY_SCOPE_AGENT); }
; __device__ __forceinline__ unsigned xb_add(unsigned* p, unsigned v) { return __hip_atomic_fetch_add(p, v, __ATOMIC_RELAXED, __HIP_MEMORY_SCOPE_AGENT); }
; #define XB_SPIN(cond, bar) do { unsigned _sp = 0; while (cond) { __builtin_amdgcn_s_sleep(1); \
;     if ((++_sp & 255u) == 0u) { if (xb_ld(&(bar)[XB_TMO])) break; if (_sp > XB_SPIN_CAP) { atomicAdd(&(bar)[XB_TMO], 1u); break; } } } } while (0)
; #define SEAM(k) do { if (IN(k) && IN((k) + 1)) xcd_barrier(bar); } while (0)
; __device__ __forceinline__ void xcd_barrier(const XcdBarrier& b) {
;     asm volatile("s_waitcnt vmcnt(0)" ::: "memory");
;     __syncthreads();
;     if (threadIdx.x == 0) {
;         unsigned* bar = b.bar;
;         __builtin_amdgcn_s_waitcnt(0);
;         unsigned nloc = b.st[0], nx = b.st[1];
;         if (nloc == 0u) { xcd_barrier_complete(bar, b.x, nloc, nx); b.st[0] = nloc; b.st[1] = nx; }
;         const unsigned old = xb_add(&bar[XB_XSUB(b.x)], 1u);
;         const unsigned gen = old / nloc;
;         if (old + 1u == (gen + 1u) * nloc) {
;             __builtin_amdgcn_fence(__ATOMIC_RELEASE, "agent");
;             asm volatile("s_waitcnt vmcnt(0)" ::: "memory");
;             const unsigned og = xb_add(&bar[XB_TOP], 1u);
;             const unsigned tg = og / nx;
;             if (og + 1u == (tg + 1u) * nx) xb_add(&bar[XB_TOPGEN], 1u);
;             else XB_SPIN(xb_ld(&bar[XB_TOPGEN]) == tg, bar);
;             __builtin_amdgcn_fence(__ATOMIC_ACQUIRE, "agent");
;             xb_add(&bar[XB_XGEN(b.x)], 1u);
;             asm volatile("s_waitcnt vmcnt(0)" ::: "memory");
;         } else {
;             XB_SPIN(xb_ld(&bar[XB_XGEN(b.x)]) == gen, bar);
;             __builtin_amdgcn_fence(__ATOMIC_ACQUIRE, "agent");
;             asm volatile("s_waitcnt vmcnt(0)" ::: "memory");
;         }
;     }
;     __syncthreads();
; }
; __global__ void __launch_bounds__(NWAVES * 64, 2) mega_fwd(Args args) {
;     ...
;     SEAM(10);
;     if (IN(11)) { pg8::Gemm g{ACT, W2d, M, DM, FF, 64, FF, 0, 0, 1, (size_t)256 * 64 * 2, (size_t)(FF / 64) * 256 * 64 * 2}; pg8::StaticOrder S; S.init(M, DM, 1, G, bx);
;         pg8::EpiResid<true> E{nullptr, XB, ss3, 0.5f}; pg8::gemm_phase<pg8::EpiResid<true>, true>(lds, g, S, E); }
.LBB0_1327:
	s_cmp_gt_i32 s85, 11
	s_cselect_b64 s[2:3], -1, 0
	s_and_b64 s[0:1], s[0:1], s[2:3]
	v_readlane_b32 s48, v252, 22
	s_andn2_b64 vcc, exec, s[0:1]
	v_readlane_b32 s49, v252, 23
	s_cbranch_vccnz .LBB0_1381
	s_waitcnt vmcnt(0)
	s_waitcnt vmcnt(0) lgkmcnt(0)
	s_barrier
	s_and_saveexec_b64 s[0:1], s[74:75]
	s_cbranch_execz .LBB0_1380
	s_getreg_b32 s4, hwreg(HW_REG_XCC_ID, 0, 4)
	s_and_b32 s4, s4, 7
	s_lshl_b32 s4, s4, 8
	s_add_u32 s6, s66, 0xfd09000
	s_addc_u32 s7, s67, 0
	v_mov_b32_e32 v1, s4
	v_mov_b32_e32 v2, 1
	v_mov_b32_e32 v4, 0x20160
	ds_read_b32 v4, v4
	global_atomic_add v1, v2, s[6:7]
	s_waitcnt lgkmcnt(0)
	v_readfirstlane_b32 s5, v4
	s_mov_b32 s8, 0
	s_nop 2
	s_mul_i32 s5, s5, 3

; __device__ __forceinline__ unsigned xb_ld(unsigned* p)              { return __hip_atomic_load(p, __ATOMIC_RELAXED, __HIP_MEMORY_SCOPE_AGENT); }
; __device__ __forceinline__ unsigned xb_add(unsigned* p, unsigned v) { return __hip_atomic_fetch_add(p, v, __ATOMIC_RELAXED, __HIP_MEMORY_SCOPE_AGENT); }
; #define XB_SPIN(cond, bar) do { unsigned _sp = 0; while (cond) { __builtin_amdgcn_s_sleep(1); \
;     if ((++_sp & 255u) == 0u) { if (xb_ld(&(bar)[XB_TMO])) break; if (_sp > XB_SPIN_CAP) { atomicAdd(&(bar)[XB_TMO], 1u); break; } } } } while (0)
; #define SEAM(k) do { if (IN(k) && IN((k) + 1)) xcd_barrier(bar); } while (0)
; __device__ __forceinline__ void xcd_barrier(const XcdBarrier& b) {
;     asm volatile("s_waitcnt vmcnt(0)" ::: "memory");
;     __syncthreads();
;     if (threadIdx.x == 0) {
;         unsigned* bar = b.bar;
;         __builtin_amdgcn_s_waitcnt(0);
;         unsigned nloc = b.st[0], nx = b.st[1];
;         if (nloc == 0u) { xcd_barrier_complete(bar, b.x, nloc, nx); b.st[0] = nloc; b.st[1] = nx; }
;         const unsigned old = xb_add(&bar[XB_XSUB(b.x)], 1u);
;         const unsigned gen = old / nloc;
;         if (old + 1u == (gen + 1u) * nloc) {
;             __builtin_amdgcn_fence(__ATOMIC_RELEASE, "agent");
;             asm volatile("s_waitcnt vmcnt(0)" ::: "memory");
;             const unsigned og = xb_add(&bar[XB_TOP], 1u);
;             const unsigned tg = og / nx;
;             if (og + 1u == (tg + 1u) * nx) xb_add(&bar[XB_TOPGEN], 1u);
;             else XB_SPIN(xb_ld(&bar[XB_TOPGEN]) == tg, bar);
;             __builtin_amdgcn_fence(__ATOMIC_ACQUIRE, "agent");
;             xb_add(&bar[XB_XGEN(b.x)], 1u);
;             asm volatile("s_waitcnt vmcnt(0)" ::: "memory");
;         } else {
;             XB_SPIN(xb_ld(&bar[XB_XGEN(b.x)]) == gen, bar);
;             __builtin_amdgcn_fence(__ATOMIC_ACQUIRE, "agent");
;             asm volatile("s_waitcnt vmcnt(0)" ::: "memory");
;         }
;     }
;     __syncthreads();
; }
; __global__ void __launch_bounds__(NWAVES * 64, 2) mega_fwd(Args args) {
;     ...
;     SEAM(11);
;     if (IN(12)) { pg8::StaticOrder S; S.init(M, DM, 1, G, bx);
;         { pg8::Gemm g{XB, Wpg, M, DM, DM, DM, DM, 0, 0, 1}; pg8::EpiPle2 E{ss3, PTMP, XB, out}; pg8::gemm_phase<pg8::EpiPle2, true>(lds, g, S, E); } }
.LBB0_1428:
	s_cmp_gt_i32 s85, 12
	s_cselect_b64 s[2:3], -1, 0
	s_and_b64 s[0:1], s[0:1], s[2:3]
	s_andn2_b64 vcc, exec, s[0:1]
	s_cbranch_vccnz .LBB0_1482
	s_waitcnt vmcnt(0)
	s_waitcnt vmcnt(0) lgkmcnt(0)
	s_barrier
	s_and_saveexec_b64 s[0:1], s[74:75]
	s_cbranch_execz .LBB0_1481
	s_getreg_b32 s4, hwreg(HW_REG_XCC_ID, 0, 4)
	s_and_b32 s4, s4, 7
	s_lshl_b32 s4, s4, 8
	s_add_u32 s6, s66, 0xfd09000
	s_addc_u32 s7, s67, 0
	v_mov_b32_e32 v1, s4
	v_mov_b32_e32 v2, 1
	v_mov_b32_e32 v4, 0x20160
	ds_read_b32 v4, v4
	global_atomic_add v1, v2, s[6:7]
	s_waitcnt lgkmcnt(0)
	v_readfirstlane_b32 s5, v4
	s_mov_b32 s8, 0
	s_nop 2
	s_mul_i32 s5, s5, 4
